# grid barrier: acquire invalidate (buffer_inv sc1) issued right after the arrival atomic returns instead of after the poll, so it overlaps the wait
# speedup vs baseline: 1.0008x; 1.0008x over previous
; __device__ __forceinline__ void grid_barrier(unsigned* bar, unsigned k, unsigned info, int swave) {
;     ...
;       const unsigned old = __hip_atomic_fetch_add(bar + 64 * (8 + myxcc), 1u, __ATOMIC_RELAXED, __HIP_MEMORY_SCOPE_AGENT);
;       if (old + 1u == k * nmine) {
;         __builtin_amdgcn_fence(__ATOMIC_RELEASE, "agent");
;         asm volatile("s_waitcnt vmcnt(0)" ::: "memory");
;         __hip_atomic_fetch_add(bar + 64 * 16, 1u, __ATOMIC_RELAXED, __HIP_MEMORY_SCOPE_AGENT);
;       }
.LBB0_30:
	s_or_b64 exec, exec, s[2:3]
	s_waitcnt vmcnt(0)
	buffer_inv sc1
	v_readfirstlane_b32 s2, v1
	v_readlane_b32 s3, v247, 43
	s_nop 0
	v_add3_u32 v0, s2, v0, 1
	v_readlane_b32 s2, v248, 60
	s_mul_i32 s2, s3, s2
	s_nop 0
	v_cmp_eq_u32_e32 vcc, s2, v0
	s_and_saveexec_b64 s[2:3], vcc
	s_cbranch_execz .LBB0_33
	s_mov_b64 s[4:5], exec
	v_mbcnt_lo_u32_b32 v0, s4, 0
	buffer_wbl2 sc1
	s_waitcnt vmcnt(0)
	v_mbcnt_hi_u32_b32 v0, s5, v0
	v_cmp_eq_u32_e32 vcc, 0, v0
	s_and_b64 s[6:7], exec, vcc
	s_mov_b64 exec, s[6:7]
	s_cbranch_execz .LBB0_33
	s_bcnt1_i32_b64 s4, s[4:5]
	v_mov_b32_e32 v0, s4
	global_atomic_add v3, v0, s[86:87]

; __device__ __forceinline__ void grid_barrier(unsigned* bar, unsigned k, unsigned info, int swave) {
;     ...
;       while (__hip_atomic_load(bar + 64 * 16, __ATOMIC_RELAXED, __HIP_MEMORY_SCOPE_AGENT) < k * nxcc) __builtin_amdgcn_s_sleep(1);
;       __builtin_amdgcn_fence(__ATOMIC_ACQUIRE, "agent");
;       asm volatile("s_waitcnt vmcnt(0)" ::: "memory");
;     }
;   }
;   __syncthreads();
.LBB0_34:
	s_sleep 1
	global_load_dword v0, v3, s[86:87] sc1
	s_waitcnt vmcnt(0)
	v_cmp_gt_u32_e32 vcc, s2, v0
	s_cbranch_vccnz .LBB0_34
.LBB0_35:
	s_waitcnt vmcnt(0)
.LBB0_36:
	s_or_b64 exec, exec, s[0:1]
